# P1 conversion deal tuned: 5 items per wave on the 64 workgroups without an ada item, at most one on the others
# baseline (speedup 1.0000x reference)
; __device__ __forceinline__ void phase1(LAS unsigned char* lds, const Params& P) {
;     ...
;     for (int it = gw; it < I_IN + I_OUT + I_LRU; it += NGW) {
;         int r = it;
;         if (r < I_IN) { p0_transpose_item<true>(P.w_in, DM, DIN, WinT, 1.0f, scr, r, lane); continue; } r -= I_IN;
;         if (r < I_OUT) { p0_transpose_item(P.w_out, 2 * DM, DM, WoutT, 1.0f, scr, r, lane); continue; } r -= I_OUT;
;         { const int mat = r >> 3, sub = r & 7, dir = mat >> 4, gate = (mat >> 3) & 1, h = mat & 7;
;           const float* src = (gate ? P.lru_wx : P.lru_wa) + (size_t)(dir * 8 + h) * 16384;
;           p0_transpose_item(src, 128, 128, LruW + (size_t)((dir * 2 + gate) * 8 + h) * 16384, -LOG2E, scr, sub, lane); }
;     }
.LBB0_33:
	s_waitcnt vmcnt(5)
	v_mov_b32_e32 v17, v167
	s_nop 0
	v_readfirstlane_b32 s79, v17
	s_ashr_i32 s0, s79, 6
	v_and_b32_e32 v162, 63, v17
	s_add_i32 s78, s0, s2
	s_cmpk_gt_i32 s78, 0xeff
	v_lshlrev_b32_e32 v16, 3, v162
	s_cbranch_scc1 .LBB0_52
	s_lshl_b32 s1, s0, 14
	v_lshrrev_b32_e32 v18, 5, v162
	v_and_b32_e32 v19, 31, v17
	s_add_i32 s1, s1, 0
	v_lshlrev_b32_e32 v4, 2, v19
	v_mul_u32_u24_e32 v0, 0x84, v18
	s_waitcnt vmcnt(4)
	v_lshrrev_b32_e32 v21, 3, v162
	v_and_b32_e32 v6, 56, v16
	v_add3_u32 v20, s1, v4, v0
	v_mul_u32_u24_e32 v0, 0x84, v6
	v_lshlrev_b32_e32 v1, 2, v21
	v_add3_u32 v22, s1, v0, v1
	s_bfe_u32 s1, s79, 0x30006
	s_lshl_b32 s44, s1, 5
	s_add_i32 s76, s44, 0xff80
	s_cmp_lt_u32 s1, 4
	s_cselect_b32 s1, s44, s76
	s_and_b32 s1, s1, 0xffe0
	v_or_b32_e32 v23, 8, v21
	v_or_b32_e32 v5, s1, v21
	v_or_b32_e32 v24, 16, v21
	v_lshlrev_b32_e32 v8, 7, v5
	v_or_b32_e32 v5, s1, v23
	v_or_b32_e32 v25, 24, v21
	v_lshlrev_b32_e32 v10, 7, v5
	v_or_b32_e32 v5, s1, v24
	v_lshlrev_b32_e32 v12, 7, v5
	v_or_b32_e32 v5, s1, v25
	v_lshlrev_b32_e32 v160, 1, v6
	v_lshlrev_b32_e32 v14, 7, v5
	v_mov_b32_e32 v5, v161
	s_lshl_b32 s0, s0, 5
	v_lshl_add_u64 v[0:1], s[18:19], 0, v[160:161]
	v_lshl_add_u64 v[2:3], s[20:21], 0, v[160:161]
	v_or_b32_e32 v26, s1, v19
	v_lshl_add_u64 v[4:5], s[50:51], 0, v[4:5]
	s_add_i32 s80, s27, s0
	v_lshlrev_b32_e32 v6, 1, v6
	v_lshlrev_b32_e32 v8, 1, v8
	v_lshlrev_b32_e32 v10, 1, v10
	v_lshlrev_b32_e32 v12, 1, v12
	v_lshlrev_b32_e32 v14, 1, v14
	v_add_u32_e32 v27, 0x400, v20
	v_add_u32_e32 v28, 0x800, v20
	v_add_u32_e32 v29, 0xc00, v20
	v_add_u32_e32 v30, 0x1000, v20
	v_add_u32_e32 v31, 0x1400, v20
	v_add_u32_e32 v32, 0x1800, v20
	v_add_u32_e32 v33, 0x1c00, v20
	s_cmpk_lt_i32 s78, 0x600
	s_cbranch_scc1 .Lp1_cv_p0
	s_add_i32 s81, s78, 0xfffffa00
	s_movk_i32 s98, 0x200
	s_movk_i32 s100, 0x9ff
	s_branch .Lp1_cv_go
.Lp1_cv_p0:
	s_add_i32 s81, s78, 0xa00
	s_movk_i32 s98, 0x600
	s_movk_i32 s100, 0xeff
.Lp1_cv_go:
	s_lshl_b32 s80, s81, 5
	s_lshl_b32 s99, s98, 5
	s_cmp_gt_i32 s81, s100
	s_cbranch_scc1 .LBB0_52
	s_branch .LBB0_37
